# P2 round 0: heavier v tiles moved to the workgroups that own three units, lighter u tiles to the two-unit workgroups that also run the sample-row GEMM (pn ^= 2 for the first unit)
# baseline (speedup 1.0000x reference)
;     __device__ bool next(int i, Unit& u) const {
;         const long L = (long)i * G + c; if (L >= nwg) return false;
;         int wgid = (int)L; { const int q = nwg / NXCD, r = nwg % NXCD, xcd = wgid % NXCD, off = wgid / NXCD; wgid = (xcd < r ? xcd * (q + 1) : r * (q + 1) + (xcd - r) * q) + off; }
;         const int nig = wgm * nN, gid = wgid / nig, fm = gid * wgm, gsz = (nM - fm) < wgm ? (nM - fm) : wgm;
;         u.pm = fm + ((wgid % nig) % gsz); u.pn = (wgid % nig) / gsz; return true;
.LBB0_201:
	s_or_b64 exec, exec, s[0:1]
	v_mov_b32_e32 v8, v224
	s_cmpk_lt_i32 s2, 0x280
	s_waitcnt lgkmcnt(0)
	s_barrier
	s_cselect_b64 s[6:7], -1, 0
	s_cmpk_gt_i32 s2, 0x27f
	v_readfirstlane_b32 s8, v8
	s_cbranch_scc1 .LBB0_203
	s_ashr_i32 s0, s2, 31
	s_lshr_b32 s0, s0, 29
	s_add_i32 s0, s2, s0
	s_ashr_i32 s1, s0, 3
	s_and_b32 s0, s0, -8
	s_sub_i32 s0, s2, s0
	s_cmp_lt_i32 s0, 0
	s_movk_i32 s4, 0x51
	s_cselect_b32 s4, s4, 0x50
	s_mul_i32 s0, s0, s4
	s_add_i32 s0, s0, s1
	s_mul_hi_i32 s1, s0, 0x66666667
	s_lshr_b32 s4, s1, 31
	s_ashr_i32 s1, s1, 5
	s_add_i32 s1, s1, s4
	s_lshl_b32 s4, s1, 3
	s_mulk_i32 s1, 0x50
	s_sub_i32 s0, s0, s1
	s_bfe_i32 s1, s0, 0x80000
	s_bfe_u32 s1, s1, 0x3000c
	s_add_i32 s1, s0, s1
	s_bfe_i32 s5, s1, 0x80000
	s_and_b32 s1, s1, 0xf8
	s_sub_i32 s0, s0, s1
	s_sext_i32_i16 s5, s5
	s_sext_i32_i8 s0, s0
	s_add_i32 s4, s4, s0
	s_ashr_i32 s0, s5, 3
	s_cmp_lt_u32 s0, 4
	s_cselect_b32 s1, 2, 0
	s_cmpk_lg_i32 s34, 0x100
	s_cselect_b32 s1, 0, s1
	s_xor_b32 s0, s0, s1
